# team barrier at eight row-local seams; the layer-1 in-proj seam is a grid barrier again (its proj writes alias other panels' act rows that down-proj of slower teams may still read)
# baseline (speedup 1.0000x reference)
.Ltb_noreg:
	s_mov_b32 s2, 0xf0780
	s_bitcmp1_b32 s2, s80
	s_cbranch_scc0 .Ltb_grid
	s_bfm_b32 s3, s80, 0
	s_and_b32 s3, s3, s2
	s_bcnt1_i32_b32 s3, s3
	s_add_i32 s3, s3, 1
	s_lshl_b32 s19, s3, 2
	v_readlane_b32 s6, v254, 44
	v_readlane_b32 s7, v254, 45
	s_bfe_u32 s13, s61, 0x60003
	s_and_b32 s14, s13, 7
	s_lshr_b32 s13, s13, 3
	s_lshl_b32 s15, s14, 3
	s_add_u32 s15, s15, s13
	s_lshl_b32 s14, s14, 6
	s_lshl_b32 s13, s13, 2
	s_add_u32 s14, s14, s13
	s_add_u32 s14, s14, 0x300
	s_add_u32 s12, s6, s14
	s_addc_u32 s13, s7, 0
	s_cmp_lg_u32 s80, 7
	s_cbranch_scc1 .Ltb_cached
	s_lshl_b32 s15, s15, 2
	s_add_u32 s15, s15, 0x200
	s_add_u32 s16, s6, s15
	s_addc_u32 s17, s7, 0
	v_readlane_b32 s20, v254, 40
	s_sub_u32 s20, s20, s6
	s_add_u32 s20, s20, 0x2000
	s_lshr_b32 s20, s20, 8
	s_lshl_b32 s20, s20, 2
	s_lshl_b32 s20, 4, s20
	global_load_dword v4, v129, s[16:17] sc1
	s_waitcnt vmcnt(0)
	v_readfirstlane_b32 s21, v4
	s_cmp_eq_u32 s21, s20
	s_cselect_b32 s21, 1, 0
	v_writelane_b32 v255, s21, 45
	s_branch .Ltb_haveflag
